# sample-FoX: the once-read f32 K/V cache rows are fetched with the nt cache policy
# speedup vs baseline: 1.0086x; 1.0086x over previous
.LBB0_979:
	s_ashr_i32 s8, s54, 3
	s_ashr_i32 s9, s8, 31
	s_lshl_b64 s[6:7], s[8:9], 6
	s_add_u32 s10, s6, 0x4000
	s_addc_u32 s11, s7, 0
	s_lshl_b64 s[6:7], s[10:11], 10
	s_add_u32 s6, s78, s6
	s_addc_u32 s7, s79, s7
	s_lshl_b32 s12, s54, 6
	s_and_b32 s30, s12, 0x1c0
	v_readlane_b32 s56, v245, 0
	s_lshl_b32 s55, s30, 1
	v_readlane_b32 s57, v245, 1
	s_add_u32 s6, s6, s55
	v_readlane_b32 s58, v245, 2
	v_readlane_b32 s59, v245, 3
	v_readlane_b32 s60, v245, 4
	v_readlane_b32 s61, v245, 5
	v_readlane_b32 s62, v245, 6
	v_readlane_b32 s63, v245, 7
	s_mov_b64 s[44:45], s[56:57]
	s_addc_u32 s7, s7, 0
	s_lshl_b64 s[36:37], s[8:9], 21
	s_lshl_b64 s[12:13], s[8:9], 23
	s_mov_b64 s[48:49], s[60:61]
	s_add_u32 s12, s48, s12
	s_addc_u32 s13, s49, s13
	s_lshl_b32 s43, s30, 2
	s_add_u32 s12, s12, s43
	s_addc_u32 s13, s13, 0
	s_mul_i32 s30, s54, 0x4100
	v_mov_b32_e32 v4, v0
	s_mul_hi_i32 s31, s54, 0x4100
	s_add_u32 s30, s84, s30
	s_addc_u32 s31, s85, s31
	v_readfirstlane_b32 s38, v4
	s_ashr_i32 s38, s38, 6
	s_lshr_b32 s39, s38, 31
	s_add_i32 s40, s38, s39
	s_ashr_i32 s39, s40, 1
	s_and_b32 s40, s40, -2
	s_sub_i32 s42, s38, s40
	s_mov_b64 s[46:47], s[58:59]
	s_mov_b64 s[50:51], s[62:63]
	v_and_b32_e32 v133, 31, v4
	s_lshl_b32 s56, s42, 5
	v_or_b32_e32 v130, s56, v133
	v_ashrrev_i32_e32 v131, 31, v130
	v_bfe_u32 v1, v4, 5, 1
	v_lshlrev_b64 v[2:3], 10, v[130:131]
	v_lshl_add_u64 v[2:3], s[6:7], 0, v[2:3]
	v_lshlrev_b32_e32 v26, 4, v1
	v_mov_b32_e32 v27, v199
	v_lshl_add_u64 v[2:3], v[2:3], 0, v[26:27]
	global_load_dwordx4 v[6:9], v[2:3], off
	global_load_dwordx4 v[10:13], v[2:3], off offset:32
	global_load_dwordx4 v[14:17], v[2:3], off offset:64
	global_load_dwordx4 v[18:21], v[2:3], off offset:96
	s_lshl_b32 s6, s42, 12
	v_and_b32_e32 v139, 63, v4
	s_add_i32 s6, s6, 0
	s_add_i32 s6, s6, 0x12400
	v_lshlrev_b32_e32 v2, 4, v139
	v_add_u32_e32 v172, s6, v2
	v_lshl_add_u64 v[2:3], v[130:131], 2, s[30:31]
	v_add_co_u32_e32 v2, vcc, s0, v2
	v_cmp_gt_i32_e64 s[6:7], s91, v4
	s_nop 0
	v_addc_co_u32_e32 v3, vcc, 0, v3, vcc
	v_mov_b32_e32 v173, 0
	s_waitcnt vmcnt(0)
	v_mov_b32_e32 v174, 0
	v_readlane_b32 s64, v245, 8
	v_readlane_b32 s65, v245, 9
	v_readlane_b32 s66, v245, 10
	v_readlane_b32 s67, v245, 11
	v_readlane_b32 s68, v245, 12
	v_readlane_b32 s69, v245, 13
	v_readlane_b32 s70, v245, 14
	v_readlane_b32 s71, v245, 15
	s_waitcnt vmcnt(0)
	ds_write_b128 v172, v[6:9]
	ds_write_b128 v172, v[10:13] offset:1024
	ds_write_b128 v172, v[14:17] offset:2048
	ds_write_b128 v172, v[18:21] offset:3072
	v_ashrrev_i32_e32 v6, 3, v4
	v_ashrrev_i32_e32 v7, 31, v6
	global_load_dword v2, v[2:3], off
	v_and_b32_e32 v3, 7, v4
	v_lshlrev_b64 v[8:9], 11, v[6:7]
	v_lshl_add_u64 v[8:9], s[12:13], 0, v[8:9]
	v_lshlrev_b32_e32 v198, 4, v3
	v_lshl_add_u64 v[8:9], v[8:9], 0, v[198:199]
	v_add_co_u32_e32 v10, vcc, 0x20000, v8
	global_load_dwordx4 v[74:77], v[8:9], off nt
	global_load_dwordx4 v[78:81], v[8:9], off offset:128 nt
	v_addc_co_u32_e32 v11, vcc, 0, v9, vcc
	global_load_dwordx4 v[66:69], v[10:11], off nt
	global_load_dwordx4 v[70:73], v[10:11], off offset:128 nt
	v_add_co_u32_e32 v10, vcc, 0x40000, v8
	s_nop 1
	v_addc_co_u32_e32 v11, vcc, 0, v9, vcc
	v_add_co_u32_e32 v8, vcc, 0x60000, v8
	global_load_dwordx4 v[82:85], v[10:11], off nt
	global_load_dwordx4 v[86:89], v[10:11], off offset:128 nt
	v_addc_co_u32_e32 v9, vcc, 0, v9, vcc
	global_load_dwordx4 v[90:93], v[8:9], off nt
	global_load_dwordx4 v[94:97], v[8:9], off offset:128 nt
	s_and_saveexec_b64 s[40:41], s[6:7]
	s_cbranch_execz .LBB0_981
	v_ashrrev_i32_e32 v5, 31, v4
	v_lshl_add_u64 v[8:9], v[4:5], 2, s[30:31]
	global_load_dword v174, v[8:9], off
.LBB0_981:
	s_or_b64 exec, exec, s[40:41]
	s_lshl_b64 s[8:9], s[8:9], 17
	s_add_u32 s40, s4, s8
	s_addc_u32 s41, s5, s9
	s_add_u32 s44, s40, s43
	v_readlane_b32 s60, v245, 0
	s_addc_u32 s45, s41, 0
	s_lshl_b64 s[36:37], s[36:37], 2
	v_readlane_b32 s66, v245, 6
	v_readlane_b32 s67, v245, 7
	s_add_u32 s36, s66, s36
	s_addc_u32 s37, s67, s37
	s_add_u32 s36, s36, s43
	s_addc_u32 s37, s37, 0
	s_add_u32 s8, s14, s8
	s_addc_u32 s9, s15, s9
	v_lshlrev_b64 v[8:9], 9, v[6:7]
	v_lshlrev_b32_e32 v5, 2, v3
	s_add_u32 s48, s8, s43
	s_addc_u32 s49, s9, 0
	s_add_i32 s8, s56, 0x1000
	v_lshl_add_u64 v[8:9], v[8:9], 2, s[36:37]
	v_lshlrev_b32_e32 v198, 2, v5
	v_or_b32_e32 v175, s8, v133
	v_lshl_add_u64 v[8:9], v[8:9], 0, v[198:199]
	s_mov_b32 s8, 0x20000
	v_readlane_b32 s68, v245, 8
	v_add_co_u32_e32 v10, vcc, s8, v8
	s_mov_b32 s68, 0x40000
	s_nop 0
	v_addc_co_u32_e32 v11, vcc, 0, v9, vcc
	global_load_dwordx4 v[106:109], v[8:9], off nt
	global_load_dwordx4 v[110:113], v[8:9], off offset:128 nt
	global_load_dwordx4 v[98:101], v[10:11], off nt
	global_load_dwordx4 v[102:105], v[10:11], off offset:128 nt
	v_add_co_u32_e32 v10, vcc, s68, v8
	s_mov_b32 s8, 0x60000
	s_nop 0
	v_addc_co_u32_e32 v11, vcc, 0, v9, vcc
	v_add_co_u32_e32 v8, vcc, s8, v8
	global_load_dwordx4 v[114:117], v[10:11], off nt
	global_load_dwordx4 v[118:121], v[10:11], off offset:128 nt
	v_addc_co_u32_e32 v9, vcc, 0, v9, vcc
	global_load_dwordx4 v[122:125], v[8:9], off nt
	global_load_dwordx4 v[126:129], v[8:9], off offset:128 nt
	s_lshl_b32 s43, s39, 6
	v_lshlrev_b32_e32 v49, 2, v1
	v_lshrrev_b32_e32 v12, 2, v4
	v_or_b32_e32 v132, s43, v49
	v_and_or_b32 v1, v12, 3, v132
	v_mul_lo_u32 v1, v1, s82
	v_add_u32_e32 v25, 0, v1
	v_and_b32_e32 v1, 16, v4
	v_lshlrev_b32_e32 v176, 2, v4
	v_or_b32_e32 v5, s43, v133
	v_and_or_b32 v1, v176, 12, v1
	v_mul_lo_u32 v5, v5, s82
	v_lshlrev_b32_e32 v27, 1, v1
	v_mul_lo_u32 v1, v6, s82
	v_add_u32_e32 v23, 0, v5
	v_lshlrev_b32_e32 v28, 2, v132
	v_add_u32_e32 v29, 0, v1
	v_lshlrev_b32_e32 v30, 3, v3
	s_mov_b64 s[8:9], 0x100
	v_mov_b32_e32 v18, v199
	v_mov_b32_e32 v19, v199
	v_add_u32_e32 v138, 0x100, v4
	v_lshl_add_u64 v[142:143], v[6:7], 0, s[8:9]
	v_mov_b32_e32 v4, v199
	v_mov_b32_e32 v5, v199
	v_mov_b32_e32 v6, v199
	v_mov_b32_e32 v7, v199
	v_mov_b32_e32 v8, v199
	v_mov_b32_e32 v9, v199
	v_mov_b32_e32 v10, v199
	v_mov_b32_e32 v11, v199
	v_mov_b32_e32 v12, v199
	v_mov_b32_e32 v13, v199
	v_mov_b32_e32 v14, v199
	v_mov_b32_e32 v15, v199
	v_mov_b32_e32 v16, v199
	v_mov_b32_e32 v17, v199
	v_add_u32_e32 v177, v23, v26
	v_add_u32_e32 v23, 0, v28
	v_add_u32_e32 v179, v25, v27
	v_add_u32_e32 v180, v29, v30
	v_mov_b64_e32 v[40:41], v[18:19]
	s_waitcnt vmcnt(15)
	v_cvt_pk_bf16_f32 v134, v74, v75
	v_cvt_pk_bf16_f32 v135, v76, v77
	s_waitcnt vmcnt(14)
	v_cvt_pk_bf16_f32 v136, v78, v79
	v_cvt_pk_bf16_f32 v137, v80, v81
	s_waitcnt vmcnt(13)
	v_cvt_pk_bf16_f32 v140, v66, v67
	v_cvt_pk_bf16_f32 v141, v68, v69
	s_waitcnt vmcnt(12)
	v_cvt_pk_bf16_f32 v144, v70, v71
	v_cvt_pk_bf16_f32 v145, v72, v73
	s_waitcnt vmcnt(11)
	v_cvt_pk_bf16_f32 v146, v82, v83
	v_cvt_pk_bf16_f32 v147, v84, v85
	s_waitcnt vmcnt(10)
	v_cvt_pk_bf16_f32 v148, v86, v87
	v_cvt_pk_bf16_f32 v149, v88, v89
	s_waitcnt vmcnt(9)
	v_cvt_pk_bf16_f32 v150, v90, v91
	v_cvt_pk_bf16_f32 v151, v92, v93
	s_waitcnt vmcnt(8)
	v_cvt_pk_bf16_f32 v152, v94, v95
	v_cvt_pk_bf16_f32 v153, v96, v97
	v_lshlrev_b64 v[74:75], 11, v[142:143]
	v_lshl_add_u64 v[74:75], s[12:13], 0, v[74:75]
	v_lshl_add_u64 v[154:155], v[74:75], 0, v[198:199]
	global_load_dwordx4 v[74:77], v[154:155], off nt
	global_load_dwordx4 v[78:81], v[154:155], off offset:128 nt
	v_add_co_u32_e32 v70, vcc, 0x20000, v154
	s_nop 1
	v_addc_co_u32_e32 v71, vcc, 0, v155, vcc
	global_load_dwordx4 v[66:69], v[70:71], off nt
	s_nop 0
	global_load_dwordx4 v[70:73], v[70:71], off offset:128 nt
	v_add_co_u32_e32 v86, vcc, 0x40000, v154
	s_nop 1
	v_addc_co_u32_e32 v87, vcc, 0, v155, vcc
	global_load_dwordx4 v[82:85], v[86:87], off nt
	s_nop 0
	global_load_dwordx4 v[86:89], v[86:87], off offset:128 nt
	v_add_co_u32_e32 v94, vcc, 0x60000, v154
	s_nop 1
	v_addc_co_u32_e32 v95, vcc, 0, v155, vcc
	global_load_dwordx4 v[90:93], v[94:95], off nt
	s_nop 0
	global_load_dwordx4 v[94:97], v[94:95], off offset:128 nt
	s_mov_b32 s50, 0
	s_add_i32 s51, s56, 0x101f
	s_addk_i32 s56, 0xfc1
	v_mov_b32_e32 v1, v2
	v_mov_b32_e32 v20, v2
	v_mov_b32_e32 v3, v2
	v_mov_b32_e32 v22, v2
	v_mov_b32_e32 v21, v2
	v_mov_b32_e32 v24, v2
	v_mov_b32_e32 v181, 0xf149f2ca
	s_mov_b64 s[40:41], 0
	v_add_u32_e32 v178, 0x12000, v23
	v_mov_b32_e32 v50, 0
	v_mov_b32_e32 v51, v173
	v_mov_b32_e32 v52, v173
	v_mov_b32_e32 v53, v173
	v_mov_b32_e32 v58, 0
	v_mov_b32_e32 v59, v173
	v_mov_b32_e32 v60, v173
	v_mov_b32_e32 v61, v173
	v_mov_b32_e32 v54, 0
	v_mov_b32_e32 v55, v173
	v_mov_b32_e32 v56, v173
	v_mov_b32_e32 v57, v173
	v_mov_b32_e32 v62, 0
	v_mov_b32_e32 v63, v173
	v_mov_b32_e32 v64, v173
	v_mov_b32_e32 v65, v173
	v_mov_b32_e32 v23, v2
	v_mov_b32_e32 v42, v2
	v_mov_b32_e32 v25, v2
	v_mov_b32_e32 v44, v2
	v_mov_b32_e32 v43, v2
	v_mov_b32_e32 v46, v2
	v_mov_b32_e32 v45, v2
	v_mov_b32_e32 v48, v2
	v_mov_b32_e32 v47, v2
	v_mov_b64_e32 v[38:39], v[16:17]
	v_mov_b64_e32 v[36:37], v[14:15]
	v_mov_b64_e32 v[34:35], v[12:13]
	v_mov_b64_e32 v[32:33], v[10:11]
	v_mov_b64_e32 v[30:31], v[8:9]
	v_mov_b64_e32 v[28:29], v[6:7]
	v_mov_b64_e32 v[26:27], v[4:5]
	v_readlane_b32 s61, v245, 1
	v_readlane_b32 s62, v245, 2
	v_readlane_b32 s63, v245, 3
	v_readlane_b32 s64, v245, 4
	v_readlane_b32 s65, v245, 5
	v_readlane_b32 s69, v245, 9
	v_readlane_b32 s70, v245, 10
	v_readlane_b32 s71, v245, 11
	v_readlane_b32 s72, v245, 12
	v_readlane_b32 s73, v245, 13
	v_readlane_b32 s74, v245, 14
	v_readlane_b32 s75, v245, 15

.LBB0_1001:
	s_or_b64 exec, exec, s[8:9]
	s_cmpk_eq_i32 s40, 0xf00
	s_cselect_b32 s58, 0xfffff000, 0
	s_cselect_b32 s61, s49, s37
	s_cselect_b32 s60, s48, s36
	s_cselect_b32 s57, -1, 0
	s_add_u32 s58, s58, s40
	s_addc_u32 s59, s57, s41
	v_lshl_add_u64 v[106:107], s[58:59], 0, v[142:143]
	v_lshlrev_b64 v[106:107], 11, v[106:107]
	v_lshl_add_u64 v[106:107], s[60:61], 0, v[106:107]
	v_lshl_add_u64 v[134:135], v[106:107], 0, v[198:199]
	global_load_dwordx4 v[106:109], v[134:135], off nt
	global_load_dwordx4 v[110:113], v[134:135], off offset:128 nt
	s_add_i32 s60, s40, 0x140
	s_cmpk_gt_u32 s60, 0x103f
	s_cbranch_scc1 .Lj2_lv_done
	v_add_co_u32_e32 v102, vcc, 0x20000, v134
	s_nop 1
	v_addc_co_u32_e32 v103, vcc, 0, v135, vcc
	global_load_dwordx4 v[98:101], v[102:103], off nt
	s_nop 0
	global_load_dwordx4 v[102:105], v[102:103], off offset:128 nt
	s_add_i32 s60, s40, 0x180
	s_cmpk_gt_u32 s60, 0x103f
	s_cbranch_scc1 .Lj2_lv_done
	v_add_co_u32_e32 v118, vcc, 0x40000, v134
	s_nop 1
	v_addc_co_u32_e32 v119, vcc, 0, v135, vcc
	global_load_dwordx4 v[114:117], v[118:119], off nt
	s_nop 0
	global_load_dwordx4 v[118:121], v[118:119], off offset:128 nt
	s_add_i32 s60, s40, 0x1c0
	s_cmpk_gt_u32 s60, 0x103f
	s_cbranch_scc1 .Lj2_lv_done
	v_add_co_u32_e32 v126, vcc, 0x60000, v134
	s_nop 1
	v_addc_co_u32_e32 v127, vcc, 0, v135, vcc
	global_load_dwordx4 v[122:125], v[126:127], off nt
	s_nop 0
	global_load_dwordx4 v[126:129], v[126:127], off offset:128 nt

.Lj2_ck_go:
	v_cvt_pk_bf16_f32 v134, v74, v75
	v_cvt_pk_bf16_f32 v135, v76, v77
	v_cvt_pk_bf16_f32 v136, v78, v79
	v_cvt_pk_bf16_f32 v137, v80, v81
	v_cvt_pk_bf16_f32 v140, v66, v67
	v_cvt_pk_bf16_f32 v141, v68, v69
	v_cvt_pk_bf16_f32 v144, v70, v71
	v_cvt_pk_bf16_f32 v145, v72, v73
	v_cvt_pk_bf16_f32 v146, v82, v83
	v_cvt_pk_bf16_f32 v147, v84, v85
	v_cvt_pk_bf16_f32 v148, v86, v87
	v_cvt_pk_bf16_f32 v149, v88, v89
	v_cvt_pk_bf16_f32 v150, v90, v91
	v_cvt_pk_bf16_f32 v151, v92, v93
	v_cvt_pk_bf16_f32 v152, v94, v95
	v_cvt_pk_bf16_f32 v153, v96, v97
	s_cmp_gt_u32 s50, 14
	s_cbranch_scc1 .LBB0_1015
	s_cmpk_eq_i32 s40, 0xe00
	s_cselect_b32 s58, 0xfffff000, 0
	s_cselect_b32 s61, s45, s13
	s_cselect_b32 s60, s44, s12
	s_cselect_b32 s57, -1, 0
	s_add_u32 s58, s58, s40
	s_addc_u32 s59, s57, s41
	s_add_u32 s58, s58, 0x100
	s_addc_u32 s59, s59, 0
	v_lshl_add_u64 v[74:75], s[58:59], 0, v[142:143]
	v_lshlrev_b64 v[74:75], 11, v[74:75]
	v_lshl_add_u64 v[74:75], s[60:61], 0, v[74:75]
	v_lshl_add_u64 v[154:155], v[74:75], 0, v[198:199]
	global_load_dwordx4 v[74:77], v[154:155], off nt
	global_load_dwordx4 v[78:81], v[154:155], off offset:128 nt
	s_add_i32 s60, s40, 0x240
	s_cmpk_gt_u32 s60, 0x103f
	s_cbranch_scc1 .LBB0_1015
	v_add_co_u32_e32 v70, vcc, 0x20000, v154
	s_nop 1
	v_addc_co_u32_e32 v71, vcc, 0, v155, vcc
	global_load_dwordx4 v[66:69], v[70:71], off nt
	s_nop 0
	global_load_dwordx4 v[70:73], v[70:71], off offset:128 nt
	s_add_i32 s60, s40, 0x280
	s_cmpk_gt_u32 s60, 0x103f
	s_cbranch_scc1 .LBB0_1015
	v_add_co_u32_e32 v86, vcc, 0x40000, v154
	s_nop 1
	v_addc_co_u32_e32 v87, vcc, 0, v155, vcc
	global_load_dwordx4 v[82:85], v[86:87], off nt
	s_nop 0
	global_load_dwordx4 v[86:89], v[86:87], off offset:128 nt
	s_add_i32 s60, s40, 0x2c0
	s_cmpk_gt_u32 s60, 0x103f
	s_cbranch_scc1 .LBB0_1015
	v_add_co_u32_e32 v94, vcc, 0x60000, v154
	s_nop 1
	v_addc_co_u32_e32 v95, vcc, 0, v155, vcc
	global_load_dwordx4 v[90:93], v[94:95], off nt
	s_nop 0
	global_load_dwordx4 v[94:97], v[94:95], off offset:128 nt
